# diff-attention STEP bodies: 7 redundant instructions removed per tile (dead vmcnt waits, max canonicalizations) and K/V prefetch loads switched to scalar base + per-lane offset (10 VALU -> 3 SALU); on
# speedup vs baseline: 1.0087x; 1.0087x over previous
; __device__ __forceinline__ void scoreConst(f32x16& p0, f32x16& p1, float& m_reg, float& alpha) {
;   const float pmax = rowmax32(p0, p1);
;   alpha = 1.f;
;   if (__builtin_expect(!__all(pmax <= THRL), 0)) { const float d = fmaxf(pmax, 0.f); m_reg += d; alpha = __builtin_amdgcn_exp2f(-d);
; #pragma unroll
;     for (int r = 0; r < 16; ++r) { p0[r] -= d; p1[r] -= d; } }
; #pragma unroll
;   for (int r = 0; r < 16; ++r) p0[r] = __builtin_amdgcn_exp2f(p0[r]);
; }
.LBB0_211:
	v_exp_f32_e32 v161, v112
	v_exp_f32_e32 v163, v113
	v_exp_f32_e32 v159, v114
	v_exp_f32_e32 v162, v115
	v_exp_f32_e32 v157, v116
	v_exp_f32_e32 v160, v117
	v_exp_f32_e32 v156, v118
	v_exp_f32_e32 v158, v119
	v_exp_f32_e32 v153, v120
	v_exp_f32_e32 v155, v121
	v_exp_f32_e32 v151, v122
	v_exp_f32_e32 v154, v123
	v_exp_f32_e32 v149, v124
	v_exp_f32_e32 v152, v125
	v_exp_f32_e32 v148, v126
	v_exp_f32_e32 v150, v127
	s_sub_i32 s38, s58, s57
	s_cmp_lt_i32 s38, 3
	s_cbranch_scc1 .LBB0_231
	v_lshl_or_b32 v252, v182, 12, v168
	v_lshl_or_b32 v253, v188, 12, v168
	s_add_i32 s39, s38, -1
	v_cmp_gt_u32_e64 s[4:5], 32, v169
	s_mov_b32 s58, 2
	s_mov_b32 s37, 0x10000
	s_mov_b32 s36, 0x8000
	s_mov_b32 s34, 0

; __device__ __forceinline__ void finishSM(f32x16& p0, f32x16& p1, float alpha, float& l_reg, bf16x8& pa0, bf16x8& pa1, bf16x8& pa2, bf16x8& pa3) {
; #pragma unroll
;   for (int r = 0; r < 16; ++r) p1[r] = __builtin_amdgcn_exp2f(p1[r]);
;   float ps = 0;
; #pragma unroll
;   for (int r = 0; r < 16; ++r) ps += p0[r];
; #pragma unroll
;   for (int r = 0; r < 16; ++r) ps += p1[r];
;   { auto rr = __builtin_amdgcn_permlane32_swap(__float_as_uint(ps), __float_as_uint(ps), false, false);
;     ps = __uint_as_float(rr[0]) + __uint_as_float(rr[1]); }
;   l_reg = l_reg * alpha + ps;
;     ...
;   PK4(p0, 0, pa0); PK4(p0, 8, pa1); PK4(p1, 0, pa2); PK4(p1, 8, pa3);
;     ...
; }
; template <int NQ> __device__ __forceinline__ void qkt(f32x16& p0, f32x16& p1, const char* Ks, const bf16x8* qr, int r32, int hi, int kcolB) {
;   p0 = f32x16{}; p1 = f32x16{};
; #pragma unroll
;   for (int d0 = 0; d0 < NQ; ++d0) { const int cb = kcolB + (d0 * 16 + hi * 8) * 2;
;     bf16x8 b0 = *reinterpret_cast<const bf16x8*>(Ks + KSWZ(r32, cb));
;     bf16x8 b1 = *reinterpret_cast<const bf16x8*>(Ks + KSWZ(32 + r32, cb));
;     p0 = __builtin_amdgcn_mfma_f32_32x32x16_bf16(b0, qr[d0], p0, 0, 0, 0);
;     p1 = __builtin_amdgcn_mfma_f32_32x32x16_bf16(b1, qr[d0], p1, 0, 0, 0); }
; }
; __device__ __forceinline__ void qkt0(f32x16& p0, f32x16& p1, const char* Ks, const char* Qs, int r32, int hi, int kcolB, const f32x16& init) {
; #pragma unroll
;   for (int d0 = 0; d0 < 4; ++d0) { const int cb = kcolB + (d0 * 16 + hi * 8) * 2;
;     bf16x8 b0 = *reinterpret_cast<const bf16x8*>(Ks + KSWZ(r32, cb));
;     bf16x8 b1 = *reinterpret_cast<const bf16x8*>(Ks + KSWZ(32 + r32, cb));
;     bf16x8 qf = *reinterpret_cast<const bf16x8*>(Qs + r32 * 128 + (((2 * d0 + hi) ^ (r32 & 7)) << 4));
;     if (d0 == 0) { p0 = __builtin_amdgcn_mfma_f32_32x32x16_bf16(b0, qf, init, 0, 0, 0); p1 = __builtin_amdgcn_mfma_f32_32x32x16_bf16(b1, qf, init, 0, 0, 0); }
;     else { p0 = __builtin_amdgcn_mfma_f32_32x32x16_bf16(b0, qf, p0, 0, 0, 0); p1 = __builtin_amdgcn_mfma_f32_32x32x16_bf16(b1, qf, p1, 0, 0, 0); } }
; }
.Lstag_a:
	s_add_i32 s34, s59, 0
	v_add_u32_e32 v112, s34, v193
	v_add_u32_e32 v116, s34, v194
	ds_read_b128 v[112:115], v112 offset:16384
	ds_read_b128 v[202:205], v181
	ds_read_b128 v[206:209], v180
	ds_read_b128 v[210:213], v116 offset:16384
	v_exp_f32_e32 v234, v96
	v_add_f32_e32 v96, 0, v161
	s_waitcnt lgkmcnt(2)
	v_mfma_f32_32x32x16_bf16 v[128:143], v[112:115], v[202:205], v[80:95]
	v_add_u32_e32 v112, s34, v197
	v_add_u32_e32 v113, s34, v195
	v_add_f32_e32 v96, v163, v96
	ds_read_b128 v[214:217], v112 offset:16384
	ds_read_b128 v[218:221], v113 offset:16384
	v_add_f32_e32 v96, v159, v96
	v_add_f32_e32 v96, v162, v96
	v_add_f32_e32 v96, v157, v96
	s_waitcnt lgkmcnt(2)
	v_mfma_f32_32x32x16_bf16 v[112:127], v[210:213], v[202:205], v[80:95]
	v_add_f32_e32 v96, v160, v96
	v_add_f32_e32 v96, v156, v96
	v_add_f32_e32 v96, v158, v96
	v_add_f32_e32 v96, v153, v96
	v_add_f32_e32 v96, v155, v96
	v_add_f32_e32 v96, v151, v96
	v_add_f32_e32 v96, v154, v96
	s_waitcnt lgkmcnt(0)
	v_mfma_f32_32x32x16_bf16 v[128:143], v[218:221], v[206:209], v[128:143]
	v_add_f32_e32 v96, v149, v96
	v_add_u32_e32 v201, s34, v199
	v_add_u32_e32 v210, s34, v196
	v_exp_f32_e32 v235, v97
	v_add_f32_e32 v96, v152, v96
	ds_read_b128 v[202:205], v201 offset:16384
	ds_read_b128 v[210:213], v210 offset:16384
	ds_read_b128 v[222:225], v179
	ds_read_b128 v[226:229], v178
	v_exp_f32_e32 v236, v98
	v_mfma_f32_32x32x16_bf16 v[112:127], v[214:217], v[206:209], v[112:127]
	v_add_f32_e32 v96, v148, v96
	v_exp_f32_e32 v237, v99
	v_add_f32_e32 v96, v150, v96
	v_exp_f32_e32 v238, v100
	v_add_f32_e32 v96, v234, v96
	v_exp_f32_e32 v239, v101
	v_add_f32_e32 v96, v235, v96
	v_exp_f32_e32 v206, v102
	s_waitcnt lgkmcnt(1)
	v_mfma_f32_32x32x16_bf16 v[128:143], v[210:213], v[222:225], v[128:143]
	v_add_f32_e32 v96, v236, v96
	v_exp_f32_e32 v207, v103
	v_add_f32_e32 v96, v237, v96
	v_add_u32_e32 v201, s34, v200
	v_add_u32_e32 v230, s34, v198
	v_exp_f32_e32 v208, v104
	v_add_f32_e32 v96, v238, v96
	v_mfma_f32_32x32x16_bf16 v[112:127], v[202:205], v[222:225], v[112:127]
	ds_read_b128 v[218:221], v201 offset:16384
	ds_read_b128 v[230:233], v230 offset:16384
	v_exp_f32_e32 v209, v105
	v_add_f32_e32 v96, v239, v96
	v_exp_f32_e32 v214, v106
	v_add_f32_e32 v96, v206, v96
	v_exp_f32_e32 v215, v107
	v_add_f32_e32 v96, v207, v96
	v_exp_f32_e32 v216, v108
	v_add_f32_e32 v96, v208, v96
	v_exp_f32_e32 v210, v109
	v_add_f32_e32 v96, v209, v96
	v_exp_f32_e32 v211, v110
	s_waitcnt lgkmcnt(0)
	v_mfma_f32_32x32x16_bf16 v[128:143], v[230:233], v[226:229], v[128:143]
	v_add_f32_e32 v96, v214, v96
	v_exp_f32_e32 v111, v111
	v_add_f32_e32 v96, v215, v96
	v_add_f32_e32 v96, v216, v96
	v_add_f32_e32 v96, v210, v96
	v_add_f32_e32 v96, v211, v96
	v_add_f32_e32 v201, v111, v96
	v_mfma_f32_32x32x16_bf16 v[112:127], v[218:221], v[226:229], v[112:127]
	v_mov_b32_e32 v202, v201
	s_nop 1
	v_permlane32_swap_b32_e32 v201, v202
	v_cvt_pk_bf16_f32 v96, v161, v163
	v_cvt_pk_bf16_f32 v97, v159, v162
	v_cvt_pk_bf16_f32 v98, v157, v160
	v_cvt_pk_bf16_f32 v99, v156, v158
	v_cvt_pk_bf16_f32 v100, v153, v155
	v_cvt_pk_bf16_f32 v101, v151, v154
	v_cvt_pk_bf16_f32 v102, v149, v152
	v_cvt_pk_bf16_f32 v103, v148, v150
	v_cvt_pk_bf16_f32 v104, v234, v235
	v_cvt_pk_bf16_f32 v105, v236, v237
	v_cvt_pk_bf16_f32 v106, v238, v239
	v_cvt_pk_bf16_f32 v107, v206, v207
	v_cvt_pk_bf16_f32 v108, v208, v209
	v_cvt_pk_bf16_f32 v109, v214, v215
	v_cvt_pk_bf16_f32 v110, v216, v210
	v_cvt_pk_bf16_f32 v111, v211, v111
	s_nop 0
	v_permlane32_swap_b32_e32 v96, v98
	v_permlane32_swap_b32_e32 v97, v99
	v_permlane32_swap_b32_e32 v100, v102
	v_permlane32_swap_b32_e32 v101, v103
	v_permlane32_swap_b32_e32 v104, v106
	v_permlane32_swap_b32_e32 v105, v107
	v_permlane32_swap_b32_e32 v108, v110
	v_permlane32_swap_b32_e32 v109, v111
	v_add_u32_e32 v203, s36, v175
	ds_read_b64_tr_b16 v[148:149], v203 offset:0
	ds_read_b64_tr_b16 v[150:151], v203 offset:0x800
	ds_read_b64_tr_b16 v[152:153], v203 offset:0x1000
	ds_read_b64_tr_b16 v[154:155], v203 offset:0x1800
	ds_read_b64_tr_b16 v[156:157], v203 offset:0x2000
	ds_read_b64_tr_b16 v[158:159], v203 offset:0x2800
	ds_read_b64_tr_b16 v[160:161], v203 offset:0x3000
	ds_read_b64_tr_b16 v[162:163], v203 offset:0x3800
	s_add_i32 s34, s58, 1
	s_waitcnt lgkmcnt(0)
; __device__ __forceinline__ void pv_d0(f32x16* o, int vb, bf16x8 pa0, bf16x8 pa1, bf16x8 pa2, bf16x8 pa3) {
;   s16x4 la[4], ha[4];
;   rd8<0>(la, ha, vb); WAITDEP(0, la, ha); mma4(o[0], la, ha, pa0, pa1, pa2, pa3);
;   rd8<1>(la, ha, vb); WAITDEP(0, la, ha); mma4(o[1], la, ha, pa0, pa1, pa2, pa3);
;   rd8<2>(la, ha, vb); WAITDEP(0, la, ha); mma4(o[2], la, ha, pa0, pa1, pa2, pa3);
;   rd8<3>(la, ha, vb); WAITDEP(0, la, ha); mma4(o[3], la, ha, pa0, pa1, pa2, pa3);
; }
; template <int MODE>
; __device__ __forceinline__ void attn_unit(bf16r* P0, const bf16r* __restrict__ PKV, int rowbase, int seqL, int h, int blk, float lam,
;                                           const float* __restrict__ subg, const float* __restrict__ tsrc, char* lds) {
;   constexpr int NQ = (MODE == 0) ? 4 : 8;
;   int tid_ = threadIdx.x; asm volatile("" : "+v"(tid_));
;   const int tid = tid_, wid = __builtin_amdgcn_readfirstlane(tid >> 6), lane = tid & 63, r32 = lane & 31, hi = lane >> 5;
;   float* ws = (float*)(lds + OFF_WS) + wid * 64; float* li_l = ws; float* al_l = ws + 32;
;   float* tb = (float*)(lds + OFF_TB);
;   int qrow, kcolB, tbase, NT, colbase, gr = 0, rs = 0, qc = 0, cmap = 0;
;   float bL = 0.f, bR = 0.f;
;   if constexpr (MODE == 0) {
;     cmap = wid >> 2; qrow = blk * 128 + (wid & 3) * 32; kcolB = cmap * 128; tbase = 0; NT = seqL / KVBLK; colbase = h * 128;
;     bL = tsrc[15 * 8 + h] * LOG2E; bR = tsrc[31 * 8 + h] * LOG2E;
;     { const int rel = tid - 256, n = rel < 0 ? -rel : rel;
;       int bk = n < 8 ? n : min(15, 8 + (31 - __clz((n * n) >> 6))); if (rel > 0) bk += 16;
;       tb[tid] = tsrc[bk * 8 + h] * LOG2E; }
;   } else {
;     const int rows = seqL / 64; qrow = blk * 256 + wid * 32; kcolB = 0; colbase = 1024 + h * 128; NT = 12;
;     const int rs0 = min(max(blk * 4 - 4, 0), rows - 8); tbase = min(rs0, rows - 12);
;     gr = blk * 4 + (wid >> 1); rs = min(max(gr - 4, 0), rows - 8); qc = (wid & 1) * 32 + r32;
;     for (int i = tid; i < 15 * 128; i += 512) { const int dr = i >> 7, dc = (i & 127) - 48; tb[i] = (dc >= 0 && dc < 31) ? tsrc[(h * 15 + dr) * 31 + dc] * LOG2E : 0.f; }
;   }
;   const bf16r* Qw = P0 + (size_t)(rowbase + qrow + r32) * LD + colbase + (MODE == 0 ? cmap * 64 : 0) + hi * 8;
;   const bf16r* Kh = PKV + (size_t)rowbase * LD + h * 128; const bf16r* Vh = Kh + 1024;
;   float m_reg = -1e30f, l_reg = 0; f32x16 o[4] = {};
	s_add_i32 s60, s37, 0
	v_mfma_f32_32x32x16_bf16 v[64:79], v[96:99], v[148:151], v[64:79]
	ds_read_b64_tr_b16 v[148:149], v203 offset:0x200
	ds_read_b64_tr_b16 v[150:151], v203 offset:0xa00
	ds_read_b64_tr_b16 v[204:205], v203 offset:0x1200
	ds_read_b64_tr_b16 v[206:207], v203 offset:0x1a00
	ds_read_b64_tr_b16 v[208:209], v203 offset:0x2200
	ds_read_b64_tr_b16 v[210:211], v203 offset:0x2a00
	ds_read_b64_tr_b16 v[212:213], v203 offset:0x3200
	v_mfma_f32_32x32x16_bf16 v[64:79], v[100:103], v[152:155], v[64:79]
	ds_read_b64_tr_b16 v[214:215], v203 offset:0x3a00
	s_min_i32 s34, s34, s39
	s_waitcnt lgkmcnt(0)
	s_cmp_ge_i32 s34, s56
	s_cselect_b32 s35, s57, 0
	s_add_i32 s35, s35, s34
	s_lshl_b32 s34, s35, 6
	v_mfma_f32_32x32x16_bf16 v[64:79], v[104:107], v[156:159], v[64:79]
	v_mfma_f32_32x32x16_bf16 v[48:63], v[96:99], v[148:151], v[48:63]
	ds_read_b64_tr_b16 v[148:149], v203 offset:0x400
	ds_read_b64_tr_b16 v[150:151], v203 offset:0xc00
	ds_read_b64_tr_b16 v[152:153], v203 offset:0x1400
	ds_read_b64_tr_b16 v[154:155], v203 offset:0x1c00
	v_mfma_f32_32x32x16_bf16 v[64:79], v[108:111], v[160:163], v[64:79]
	ds_read_b64_tr_b16 v[160:161], v203 offset:0x2400
	ds_read_b64_tr_b16 v[162:163], v203 offset:0x2c00
	v_mfma_f32_32x32x16_bf16 v[48:63], v[100:103], v[204:207], v[48:63]
	ds_read_b64_tr_b16 v[204:205], v203 offset:0x3400
	ds_read_b64_tr_b16 v[206:207], v203 offset:0x3c00
	s_nop 0
	s_waitcnt lgkmcnt(0)
	ds_read_b64_tr_b16 v[216:217], v203 offset:0x600
	ds_read_b64_tr_b16 v[218:219], v203 offset:0xe00
	s_nop 0
	v_mfma_f32_32x32x16_bf16 v[32:47], v[96:99], v[148:151], v[32:47]
	s_lshl_b32 s98, s34, 12
	s_add_u32 s98, s30, s98
	s_addc_u32 s99, s31, 0
	v_mfma_f32_32x32x16_bf16 v[48:63], v[104:107], v[208:211], v[48:63]
	ds_read_b64_tr_b16 v[208:209], v203 offset:0x1600
	ds_read_b64_tr_b16 v[210:211], v203 offset:0x1e00
	ds_read_b64_tr_b16 v[220:221], v203 offset:0x2600
	ds_read_b64_tr_b16 v[222:223], v203 offset:0x2e00
	ds_read_b64_tr_b16 v[224:225], v203 offset:0x3600
	ds_read_b64_tr_b16 v[226:227], v203 offset:0x3e00
	v_mfma_f32_32x32x16_bf16 v[32:47], v[100:103], v[152:155], v[32:47]
	s_waitcnt lgkmcnt(0)
	s_waitcnt vmcnt(0)
	global_load_dwordx4 v[156:159], v252, s[98:99] offset:2048
	s_nop 0
	global_load_dwordx4 v[148:151], v252, s[98:99]
	v_add_u32_e32 v203, s60, v183
	v_mfma_f32_32x32x16_bf16 v[32:47], v[104:107], v[160:163], v[32:47]
	global_load_dwordx4 v[160:163], v253, s[98:99] offset:2048
	s_nop 0
	global_load_dwordx4 v[152:155], v253, s[98:99]
	ds_write_b128 v203, v[6:9]
	v_add_u32_e32 v6, s60, v189
	ds_write_b128 v6, v[144:147]
	v_add_u32_e32 v6, s60, v190
	ds_write_b128 v6, v[2:5] offset:16384
	v_add_u32_e32 v2, s60, v191
	v_mfma_f32_32x32x16_bf16 v[16:31], v[96:99], v[216:219], v[16:31]
	ds_write_b128 v2, v[10:13] offset:16384
	v_max_f32_e32 v2, v128, v129
	v_max3_f32 v2, v2, v130, v131
	v_max3_f32 v2, v2, v132, v133
	v_max3_f32 v2, v2, v134, v135
	v_mfma_f32_32x32x16_bf16 v[16:31], v[100:103], v[208:211], v[16:31]
	v_max3_f32 v2, v2, v136, v137
	v_max3_f32 v2, v2, v138, v139
	v_max3_f32 v2, v2, v140, v141
	v_max3_f32 v2, v2, v142, v143
	v_max3_f32 v2, v2, v112, v113
	v_max3_f32 v2, v2, v114, v115
	v_max3_f32 v2, v2, v116, v117
	v_mfma_f32_32x32x16_bf16 v[16:31], v[104:107], v[220:223], v[16:31]
	v_max3_f32 v2, v2, v118, v119
	v_max3_f32 v2, v2, v120, v121
	v_max3_f32 v2, v2, v122, v123
	v_max3_f32 v2, v2, v124, v125
	v_max3_f32 v2, v2, v126, v127
	v_mov_b32_e32 v3, v2
	s_nop 1
	v_permlane32_swap_b32_e32 v2, v3
	v_mfma_f32_32x32x16_bf16 v[48:63], v[108:111], v[212:215], v[48:63]
	v_max_f32_e32 v2, v2, v3
	v_cmp_ge_f32_e32 vcc, s49, v2
	s_cmp_eq_u64 vcc, exec
	v_mov_b32_e32 v203, 1.0
	v_mfma_f32_32x32x16_bf16 v[32:47], v[108:111], v[204:207], v[32:47]
	v_mfma_f32_32x32x16_bf16 v[16:31], v[108:111], v[224:227], v[16:31]
	s_cbranch_scc0 .LBB0_229

; __device__ __forceinline__ void finishSM(f32x16& p0, f32x16& p1, float alpha, float& l_reg, bf16x8& pa0, bf16x8& pa1, bf16x8& pa2, bf16x8& pa3) {
; #pragma unroll
;   for (int r = 0; r < 16; ++r) p1[r] = __builtin_amdgcn_exp2f(p1[r]);
;   float ps = 0;
; #pragma unroll
;   for (int r = 0; r < 16; ++r) ps += p0[r];
; #pragma unroll
;   for (int r = 0; r < 16; ++r) ps += p1[r];
;   { auto rr = __builtin_amdgcn_permlane32_swap(__float_as_uint(ps), __float_as_uint(ps), false, false);
;     ps = __uint_as_float(rr[0]) + __uint_as_float(rr[1]); }
;   l_reg = l_reg * alpha + ps;
;     ...
;   PK4(p0, 0, pa0); PK4(p0, 8, pa1); PK4(p1, 0, pa2); PK4(p1, 8, pa3);
;     ...
; }
; template <int NQ> __device__ __forceinline__ void qkt(f32x16& p0, f32x16& p1, const char* Ks, const bf16x8* qr, int r32, int hi, int kcolB) {
;   p0 = f32x16{}; p1 = f32x16{};
; #pragma unroll
;   for (int d0 = 0; d0 < NQ; ++d0) { const int cb = kcolB + (d0 * 16 + hi * 8) * 2;
;     bf16x8 b0 = *reinterpret_cast<const bf16x8*>(Ks + KSWZ(r32, cb));
;     bf16x8 b1 = *reinterpret_cast<const bf16x8*>(Ks + KSWZ(32 + r32, cb));
;     p0 = __builtin_amdgcn_mfma_f32_32x32x16_bf16(b0, qr[d0], p0, 0, 0, 0);
;     p1 = __builtin_amdgcn_mfma_f32_32x32x16_bf16(b1, qr[d0], p1, 0, 0, 0); }
; }
; __device__ __forceinline__ void qkt0(f32x16& p0, f32x16& p1, const char* Ks, const char* Qs, int r32, int hi, int kcolB, const f32x16& init) {
; #pragma unroll
;   for (int d0 = 0; d0 < 4; ++d0) { const int cb = kcolB + (d0 * 16 + hi * 8) * 2;
;     bf16x8 b0 = *reinterpret_cast<const bf16x8*>(Ks + KSWZ(r32, cb));
;     bf16x8 b1 = *reinterpret_cast<const bf16x8*>(Ks + KSWZ(32 + r32, cb));
;     bf16x8 qf = *reinterpret_cast<const bf16x8*>(Qs + r32 * 128 + (((2 * d0 + hi) ^ (r32 & 7)) << 4));
;     if (d0 == 0) { p0 = __builtin_amdgcn_mfma_f32_32x32x16_bf16(b0, qf, init, 0, 0, 0); p1 = __builtin_amdgcn_mfma_f32_32x32x16_bf16(b1, qf, init, 0, 0, 0); }
;     else { p0 = __builtin_amdgcn_mfma_f32_32x32x16_bf16(b0, qf, p0, 0, 0, 0); p1 = __builtin_amdgcn_mfma_f32_32x32x16_bf16(b1, qf, p1, 0, 0, 0); } }
; }
.Lstag_b:
	v_exp_f32_e32 v224, v128
	v_exp_f32_e32 v225, v129
	v_exp_f32_e32 v226, v130
	v_exp_f32_e32 v227, v131
	v_exp_f32_e32 v228, v132
	v_exp_f32_e32 v229, v133
	v_exp_f32_e32 v230, v134
	v_exp_f32_e32 v231, v135
	v_exp_f32_e32 v232, v136
	v_exp_f32_e32 v233, v137
	v_exp_f32_e32 v234, v138
	v_exp_f32_e32 v235, v139
	v_exp_f32_e32 v236, v140
	v_exp_f32_e32 v237, v141
	v_exp_f32_e32 v238, v142
	v_exp_f32_e32 v239, v143
	v_add_u32_e32 v2, s60, v193
	ds_read_b128 v[2:5], v2 offset:16384
	ds_read_b128 v[6:9], v181
	v_add_u32_e32 v96, s60, v194
	ds_read_b128 v[10:13], v180
	v_add_u32_e32 v97, s60, v195
	v_add_u32_e32 v208, s60, v199
	s_waitcnt lgkmcnt(1)
	v_mfma_f32_32x32x16_bf16 v[128:143], v[2:5], v[6:9], v[80:95]
	ds_read_b128 v[2:5], v96 offset:16384
	v_add_u32_e32 v96, s60, v197
	ds_read_b128 v[144:147], v96 offset:16384
	ds_read_b128 v[204:207], v97 offset:16384
	v_add_u32_e32 v209, s60, v196
	v_exp_f32_e32 v240, v114
	v_exp_f32_e32 v241, v115
	v_exp_f32_e32 v242, v116
	s_waitcnt lgkmcnt(0)
	v_mfma_f32_32x32x16_bf16 v[128:143], v[204:207], v[10:13], v[128:143]
	v_exp_f32_e32 v206, v112
	v_exp_f32_e32 v207, v113
	v_exp_f32_e32 v243, v117
	v_exp_f32_e32 v244, v118
	v_add_u32_e32 v216, s60, v200
	v_add_u32_e32 v220, s60, v198
	v_mfma_f32_32x32x16_bf16 v[96:111], v[2:5], v[6:9], v[80:95]
	ds_read_b128 v[2:5], v208 offset:16384
	ds_read_b128 v[6:9], v209 offset:16384
	ds_read_b128 v[208:211], v179
	ds_read_b128 v[212:215], v178
	ds_read_b128 v[216:219], v216 offset:16384
	ds_read_b128 v[220:223], v220 offset:16384
	v_cvt_pk_bf16_f32 v116, v224, v225
	v_cvt_pk_bf16_f32 v117, v226, v227
	v_cvt_pk_bf16_f32 v118, v228, v229
	s_nop 0
	v_permlane32_swap_b32_e32 v116, v118
	v_mfma_f32_32x32x16_bf16 v[96:111], v[144:147], v[10:13], v[96:111]
	v_exp_f32_e32 v10, v119
	v_exp_f32_e32 v11, v120
	v_exp_f32_e32 v12, v121
	v_exp_f32_e32 v13, v122
	v_exp_f32_e32 v144, v123
	v_exp_f32_e32 v145, v124
	v_exp_f32_e32 v146, v125
	s_waitcnt lgkmcnt(3)
	v_mfma_f32_32x32x16_bf16 v[128:143], v[6:9], v[208:211], v[128:143]
	v_add_f32_e32 v8, 0, v224
	v_add_f32_e32 v8, v225, v8
	v_add_f32_e32 v8, v226, v8
	v_add_f32_e32 v8, v227, v8
	v_add_f32_e32 v8, v228, v8
	v_exp_f32_e32 v6, v126
	v_exp_f32_e32 v7, v127
	v_mfma_f32_32x32x16_bf16 v[96:111], v[2:5], v[208:211], v[96:111]
	v_add_f32_e32 v2, v229, v8
	v_add_f32_e32 v2, v230, v2
	v_add_f32_e32 v2, v231, v2
	v_add_f32_e32 v2, v232, v2
	v_add_f32_e32 v2, v233, v2
	v_add_f32_e32 v2, v234, v2
	v_add_f32_e32 v2, v235, v2
	v_add_f32_e32 v2, v236, v2
	v_add_f32_e32 v2, v237, v2
	v_add_f32_e32 v2, v238, v2
	v_add_f32_e32 v2, v239, v2
	v_add_f32_e32 v2, v206, v2
	v_add_f32_e32 v2, v207, v2
	v_add_f32_e32 v2, v240, v2
	v_add_f32_e32 v2, v241, v2
	v_add_f32_e32 v2, v242, v2
	v_add_f32_e32 v2, v243, v2
	v_add_f32_e32 v2, v244, v2
	v_add_f32_e32 v2, v10, v2
	v_add_f32_e32 v2, v11, v2
	v_add_f32_e32 v2, v12, v2
	s_waitcnt lgkmcnt(0)
	v_mfma_f32_32x32x16_bf16 v[128:143], v[220:223], v[212:215], v[128:143]
	v_add_f32_e32 v2, v13, v2
	v_add_f32_e32 v2, v144, v2
	v_add_f32_e32 v2, v145, v2
	v_add_f32_e32 v2, v146, v2
	v_add_f32_e32 v2, v6, v2
	v_add_f32_e32 v204, v7, v2
	v_mov_b32_e32 v205, v204
	v_mfma_f32_32x32x16_bf16 v[96:111], v[216:219], v[212:215], v[96:111]
	v_cvt_pk_bf16_f32 v119, v230, v231
	v_cvt_pk_bf16_f32 v112, v232, v233
	v_cvt_pk_bf16_f32 v113, v234, v235
	v_cvt_pk_bf16_f32 v114, v236, v237
	v_cvt_pk_bf16_f32 v115, v238, v239
	s_nop 0
	v_permlane32_swap_b32_e32 v204, v205
	v_permlane32_swap_b32_e32 v112, v114
	v_permlane32_swap_b32_e32 v113, v115
	v_cvt_pk_bf16_f32 v120, v206, v207
	v_cvt_pk_bf16_f32 v121, v240, v241
	v_cvt_pk_bf16_f32 v122, v242, v243
	v_cvt_pk_bf16_f32 v123, v244, v10
	v_cvt_pk_bf16_f32 v124, v11, v12
	v_cvt_pk_bf16_f32 v125, v13, v144
	v_cvt_pk_bf16_f32 v126, v145, v146
	v_cvt_pk_bf16_f32 v127, v6, v7
	v_permlane32_swap_b32_e32 v117, v119
	v_permlane32_swap_b32_e32 v120, v122
	v_permlane32_swap_b32_e32 v121, v123
	v_permlane32_swap_b32_e32 v124, v126
	v_permlane32_swap_b32_e32 v125, v127
	v_add_u32_e32 v230, s59, v175
	ds_read_b64_tr_b16 v[2:3], v230 offset:0
	ds_read_b64_tr_b16 v[4:5], v230 offset:0x800
	ds_read_b64_tr_b16 v[6:7], v230 offset:0x1000
	ds_read_b64_tr_b16 v[8:9], v230 offset:0x1800
	ds_read_b64_tr_b16 v[10:11], v230 offset:0x2000
	ds_read_b64_tr_b16 v[12:13], v230 offset:0x2800
	ds_read_b64_tr_b16 v[144:145], v230 offset:0x3000
	ds_read_b64_tr_b16 v[146:147], v230 offset:0x3800
	s_add_i32 s58, s58, 2
	s_waitcnt lgkmcnt(0)
; __device__ __forceinline__ void pv_d0(f32x16* o, int vb, bf16x8 pa0, bf16x8 pa1, bf16x8 pa2, bf16x8 pa3) {
;   s16x4 la[4], ha[4];
;   rd8<0>(la, ha, vb); WAITDEP(0, la, ha); mma4(o[0], la, ha, pa0, pa1, pa2, pa3);
;   rd8<1>(la, ha, vb); WAITDEP(0, la, ha); mma4(o[1], la, ha, pa0, pa1, pa2, pa3);
;   rd8<2>(la, ha, vb); WAITDEP(0, la, ha); mma4(o[2], la, ha, pa0, pa1, pa2, pa3);
;   rd8<3>(la, ha, vb); WAITDEP(0, la, ha); mma4(o[3], la, ha, pa0, pa1, pa2, pa3);
; }
; template <int MODE>
; __device__ __forceinline__ void attn_unit(bf16r* P0, const bf16r* __restrict__ PKV, int rowbase, int seqL, int h, int blk, float lam,
;                                           const float* __restrict__ subg, const float* __restrict__ tsrc, char* lds) {
;   constexpr int NQ = (MODE == 0) ? 4 : 8;
;   int tid_ = threadIdx.x; asm volatile("" : "+v"(tid_));
;   const int tid = tid_, wid = __builtin_amdgcn_readfirstlane(tid >> 6), lane = tid & 63, r32 = lane & 31, hi = lane >> 5;
;   float* ws = (float*)(lds + OFF_WS) + wid * 64; float* li_l = ws; float* al_l = ws + 32;
;   float* tb = (float*)(lds + OFF_TB);
;   int qrow, kcolB, tbase, NT, colbase, gr = 0, rs = 0, qc = 0, cmap = 0;
;   float bL = 0.f, bR = 0.f;
;   if constexpr (MODE == 0) {
;     cmap = wid >> 2; qrow = blk * 128 + (wid & 3) * 32; kcolB = cmap * 128; tbase = 0; NT = seqL / KVBLK; colbase = h * 128;
;     bL = tsrc[15 * 8 + h] * LOG2E; bR = tsrc[31 * 8 + h] * LOG2E;
;     { const int rel = tid - 256, n = rel < 0 ? -rel : rel;
;       int bk = n < 8 ? n : min(15, 8 + (31 - __clz((n * n) >> 6))); if (rel > 0) bk += 16;
;       tb[tid] = tsrc[bk * 8 + h] * LOG2E; }
;   } else {
;     const int rows = seqL / 64; qrow = blk * 256 + wid * 32; kcolB = 0; colbase = 1024 + h * 128; NT = 12;
;     const int rs0 = min(max(blk * 4 - 4, 0), rows - 8); tbase = min(rs0, rows - 12);
;     gr = blk * 4 + (wid >> 1); rs = min(max(gr - 4, 0), rows - 8); qc = (wid & 1) * 32 + r32;
;     for (int i = tid; i < 15 * 128; i += 512) { const int dr = i >> 7, dc = (i & 127) - 48; tb[i] = (dc >= 0 && dc < 31) ? tsrc[(h * 15 + dr) * 31 + dc] * LOG2E : 0.f; }
;   }
;   const bf16r* Qw = P0 + (size_t)(rowbase + qrow + r32) * LD + colbase + (MODE == 0 ? cmap * 64 : 0) + hi * 8;
;   const bf16r* Kh = PKV + (size_t)rowbase * LD + h * 128; const bf16r* Vh = Kh + 1024;
;   float m_reg = -1e30f, l_reg = 0; f32x16 o[4] = {};
	s_add_i32 s34, s36, 0
	v_mfma_f32_32x32x16_bf16 v[64:79], v[116:119], v[2:5], v[64:79]
	ds_read_b64_tr_b16 v[2:3], v230 offset:0x200
	ds_read_b64_tr_b16 v[4:5], v230 offset:0xa00
	ds_read_b64_tr_b16 v[206:207], v230 offset:0x1200
	ds_read_b64_tr_b16 v[208:209], v230 offset:0x1a00
	ds_read_b64_tr_b16 v[210:211], v230 offset:0x2200
	ds_read_b64_tr_b16 v[212:213], v230 offset:0x2a00
	ds_read_b64_tr_b16 v[214:215], v230 offset:0x3200
	v_mfma_f32_32x32x16_bf16 v[64:79], v[112:115], v[6:9], v[64:79]
	ds_read_b64_tr_b16 v[216:217], v230 offset:0x3a00
	s_min_i32 s35, s58, s39
	s_waitcnt lgkmcnt(0)
	s_cmp_ge_i32 s35, s56
	s_cselect_b32 s60, s57, 0
	s_add_i32 s60, s60, s35
	s_lshl_b32 s35, s60, 6
	v_mfma_f32_32x32x16_bf16 v[48:63], v[116:119], v[2:5], v[48:63]
	ds_read_b64_tr_b16 v[2:3], v230 offset:0x400
	ds_read_b64_tr_b16 v[4:5], v230 offset:0xc00
	ds_read_b64_tr_b16 v[6:7], v230 offset:0x1400
	ds_read_b64_tr_b16 v[8:9], v230 offset:0x1c00
	v_mfma_f32_32x32x16_bf16 v[64:79], v[120:123], v[10:13], v[64:79]
	ds_read_b64_tr_b16 v[10:11], v230 offset:0x2400
	ds_read_b64_tr_b16 v[12:13], v230 offset:0x2c00
	v_mfma_f32_32x32x16_bf16 v[48:63], v[112:115], v[206:209], v[48:63]
	ds_read_b64_tr_b16 v[206:207], v230 offset:0x3400
	ds_read_b64_tr_b16 v[208:209], v230 offset:0x3c00
	s_nop 0
	s_waitcnt lgkmcnt(0)
	ds_read_b64_tr_b16 v[218:219], v230 offset:0x600
	ds_read_b64_tr_b16 v[220:221], v230 offset:0xe00
	s_nop 0
	v_mfma_f32_32x32x16_bf16 v[32:47], v[116:119], v[2:5], v[32:47]
	s_lshl_b32 s98, s35, 12
	s_add_u32 s98, s30, s98
	s_addc_u32 s99, s31, 0
	v_mfma_f32_32x32x16_bf16 v[48:63], v[120:123], v[210:213], v[48:63]
	ds_read_b64_tr_b16 v[210:211], v230 offset:0x1600
	ds_read_b64_tr_b16 v[212:213], v230 offset:0x1e00
	ds_read_b64_tr_b16 v[222:223], v230 offset:0x2600
	ds_read_b64_tr_b16 v[224:225], v230 offset:0x2e00
	ds_read_b64_tr_b16 v[226:227], v230 offset:0x3600
	ds_read_b64_tr_b16 v[228:229], v230 offset:0x3e00
	v_mfma_f32_32x32x16_bf16 v[32:47], v[112:115], v[6:9], v[32:47]
	s_waitcnt lgkmcnt(0)
	s_waitcnt vmcnt(0)
	v_mfma_f32_32x32x16_bf16 v[48:63], v[124:127], v[214:217], v[48:63]
	global_load_dwordx4 v[6:9], v252, s[98:99] offset:2048
	s_nop 0
	global_load_dwordx4 v[2:5], v252, s[98:99]
	v_mfma_f32_32x32x16_bf16 v[64:79], v[124:127], v[144:147], v[64:79]
	v_mfma_f32_32x32x16_bf16 v[32:47], v[120:123], v[10:13], v[32:47]
	global_load_dwordx4 v[144:147], v253, s[98:99] offset:2048
	global_load_dwordx4 v[10:13], v253, s[98:99]
	v_add_u32_e32 v214, s34, v183
	ds_write_b128 v214, v[156:159]
	v_add_u32_e32 v156, s34, v189
	ds_write_b128 v156, v[160:163]
	v_add_u32_e32 v156, s34, v190
	ds_write_b128 v156, v[148:151] offset:16384
	v_mfma_f32_32x32x16_bf16 v[16:31], v[116:119], v[218:221], v[16:31]
	v_add_u32_e32 v148, s34, v191
	ds_write_b128 v148, v[152:155] offset:16384
	v_max_f32_e32 v148, v128, v129
	v_max3_f32 v148, v148, v130, v131
	v_max3_f32 v148, v148, v132, v133
	v_mfma_f32_32x32x16_bf16 v[16:31], v[112:115], v[210:213], v[16:31]
	v_max3_f32 v116, v148, v134, v135
	v_max3_f32 v116, v116, v136, v137
	v_max3_f32 v116, v116, v138, v139
	v_max3_f32 v116, v116, v140, v141
	v_max3_f32 v116, v116, v142, v143
	v_max3_f32 v116, v116, v96, v97
	v_max3_f32 v116, v116, v98, v99
	v_mfma_f32_32x32x16_bf16 v[16:31], v[120:123], v[222:225], v[16:31]
	v_max3_f32 v112, v116, v100, v101
	v_max3_f32 v112, v112, v102, v103
	v_max3_f32 v112, v112, v104, v105
	v_max3_f32 v112, v112, v106, v107
	v_max3_f32 v112, v112, v108, v109
	v_max3_f32 v112, v112, v110, v111
	v_mov_b32_e32 v113, v112
	v_mfma_f32_32x32x16_bf16 v[32:47], v[124:127], v[206:209], v[32:47]
	s_nop 0
	v_permlane32_swap_b32_e32 v112, v113
	v_max_f32_e32 v113, v112, v113
	v_cmp_ge_f32_e32 vcc, s49, v113
	s_cmp_eq_u64 vcc, exec
	v_mfma_f32_32x32x16_bf16 v[16:31], v[124:127], v[226:229], v[16:31]
	v_mov_b32_e32 v112, 1.0
	s_cbranch_scc0 .LBB0_230

; __global__ void __launch_bounds__(NWAVES * 64, 2) mk_fwd(Args a_unused) {
	.amdhsa_kernel _Z6mk_fwd4Args
		.amdhsa_group_segment_fixed_size 0
		.amdhsa_private_segment_fixed_size 0
		.amdhsa_kernarg_size 416
		.amdhsa_user_sgpr_count 2
		.amdhsa_user_sgpr_dispatch_ptr 0
		.amdhsa_user_sgpr_queue_ptr 0
		.amdhsa_user_sgpr_kernarg_segment_ptr 1
		.amdhsa_user_sgpr_dispatch_id 0
		.amdhsa_user_sgpr_kernarg_preload_length 0
		.amdhsa_user_sgpr_kernarg_preload_offset 0
		.amdhsa_user_sgpr_private_segment_size 0
		.amdhsa_uses_dynamic_stack 0
		.amdhsa_enable_private_segment 0
		.amdhsa_system_sgpr_workgroup_id_x 1
		.amdhsa_system_sgpr_workgroup_id_y 0
		.amdhsa_system_sgpr_workgroup_id_z 0
		.amdhsa_system_sgpr_workgroup_info 0
		.amdhsa_system_vgpr_workitem_id 2
		.amdhsa_next_free_vgpr 256
		.amdhsa_next_free_sgpr 102
		.amdhsa_accum_offset 256
		.amdhsa_reserve_vcc 1
		.amdhsa_float_round_mode_32 0
		.amdhsa_float_round_mode_16_64 0
		.amdhsa_float_denorm_mode_32 3
		.amdhsa_float_denorm_mode_16_64 3
		.amdhsa_dx10_clamp 1
		.amdhsa_ieee_mode 1
		.amdhsa_fp16_overflow 0
		.amdhsa_tg_split 0
		.amdhsa_exception_fp_ieee_invalid_op 0
		.amdhsa_exception_fp_denorm_src 0
		.amdhsa_exception_fp_ieee_div_zero 0
		.amdhsa_exception_fp_ieee_overflow 0
		.amdhsa_exception_fp_ieee_underflow 0
		.amdhsa_exception_fp_ieee_inexact 0
		.amdhsa_exception_int_div_zero 0
	.end_amdhsa_kernel

; __global__ void __launch_bounds__(NWAVES * 64, 2) mk_fwd(Args a_unused) {
amdhsa.kernels:
  - .agpr_count:     0
    .args:
      - .offset:         0
        .size:           160
        .value_kind:     by_value
      - .offset:         160
        .size:           4
        .value_kind:     hidden_block_count_x
      - .offset:         164
        .size:           4
        .value_kind:     hidden_block_count_y
      - .offset:         168
        .size:           4
        .value_kind:     hidden_block_count_z
      - .offset:         172
        .size:           2
        .value_kind:     hidden_group_size_x
      - .offset:         174
        .size:           2
        .value_kind:     hidden_group_size_y
      - .offset:         176
        .size:           2
        .value_kind:     hidden_group_size_z
      - .offset:         178
        .size:           2
        .value_kind:     hidden_remainder_x
      - .offset:         180
        .size:           2
        .value_kind:     hidden_remainder_y
      - .offset:         182
        .size:           2
        .value_kind:     hidden_remainder_z
      - .offset:         200
        .size:           8
        .value_kind:     hidden_global_offset_x
      - .offset:         208
        .size:           8
        .value_kind:     hidden_global_offset_y
      - .offset:         216
        .size:           8
        .value_kind:     hidden_global_offset_z
      - .offset:         224
        .size:           2
        .value_kind:     hidden_grid_dims
      - .offset:         248
        .size:           8
        .value_kind:     hidden_multigrid_sync_arg
      - .offset:         280
        .size:           4
        .value_kind:     hidden_dynamic_lds_size
    .group_segment_fixed_size: 0
    .kernarg_segment_align: 8
    .kernarg_segment_size: 416
    .language:       OpenCL C
    .language_version:
      - 2
      - 0
    .max_flat_workgroup_size: 512
    .name:           _Z6mk_fwd4Args
    .private_segment_fixed_size: 0
    .sgpr_count:     108
    .sgpr_spill_count: 0
    .symbol:         _Z6mk_fwd4Args.kd
    .uniform_work_group_size: 1
    .uses_dynamic_stack: false
    .vgpr_count:     256
    .vgpr_spill_count: 0
    .wavefront_size: 64
